# epilogue re-alignment of the two wave groups extended to P5 (on top of P1/P7/P8)
# baseline (speedup 1.0000x reference)
.Lpeel_out_136:
	s_cmpk_gt_u32 s31, 0xff
	s_cbranch_scc1 .Lep_a_136
	s_barrier
.Lep_a_136:
	v_lshl_add_u32 v146, s0, 8, v142
	v_cvt_pk_bf16_f32 v72, v72, v73
	v_cvt_pk_bf16_f32 v73, v74, v75
	v_cvt_pk_bf16_f32 v74, v68, v69
	v_add_u32_e32 v68, 0x80, v146
	s_lshl_b32 s0, s1, 8
	v_ashrrev_i32_e32 v147, 31, v146
	v_readlane_b32 s20, v252, 12
	v_cvt_pk_bf16_f32 v112, v112, v113
	v_cvt_pk_bf16_f32 v113, v114, v115
	v_cvt_pk_bf16_f32 v114, v108, v109
	v_or_b32_e32 v108, 16, v146
	v_ashrrev_i32_e32 v69, 31, v68
	v_cvt_pk_bf16_f32 v48, v48, v49
	v_cvt_pk_bf16_f32 v49, v50, v51
	v_cvt_pk_bf16_f32 v50, v44, v45
	v_add_u32_e32 v44, 0x90, v146
	s_ashr_i32 s1, s0, 31
	v_lshlrev_b64 v[148:149], 11, v[146:147]
	v_readlane_b32 s21, v252, 13
	v_ashrrev_i32_e32 v109, 31, v108
	v_cvt_pk_bf16_f32 v96, v96, v97
	v_cvt_pk_bf16_f32 v97, v98, v99
	v_cvt_pk_bf16_f32 v98, v92, v93
	v_or_b32_e32 v92, 32, v146
	v_lshlrev_b64 v[68:69], 11, v[68:69]
	v_ashrrev_i32_e32 v45, 31, v44
	v_cvt_pk_bf16_f32 v32, v32, v33
	v_cvt_pk_bf16_f32 v33, v34, v35
	v_cvt_pk_bf16_f32 v34, v28, v29
	v_add_u32_e32 v28, 0xa0, v146
	v_lshl_add_u64 v[148:149], s[20:21], 0, v[148:149]
	s_lshl_b64 s[0:1], s[0:1], 1
	v_lshlrev_b64 v[108:109], 11, v[108:109]
	v_ashrrev_i32_e32 v93, 31, v92
	v_cvt_pk_bf16_f32 v80, v80, v81
	v_cvt_pk_bf16_f32 v81, v82, v83
	v_cvt_pk_bf16_f32 v82, v76, v77
	v_or_b32_e32 v76, 48, v146
	v_lshl_add_u64 v[68:69], s[20:21], 0, v[68:69]
	v_lshlrev_b64 v[44:45], 11, v[44:45]
	v_ashrrev_i32_e32 v29, 31, v28
	v_cvt_pk_bf16_f32 v20, v20, v21
	v_cvt_pk_bf16_f32 v21, v22, v23
	v_cvt_pk_bf16_f32 v22, v12, v13
	v_add_u32_e32 v12, 0xb0, v146
	v_lshl_add_u64 v[148:149], v[148:149], 0, s[0:1]
	v_lshl_add_u64 v[108:109], s[20:21], 0, v[108:109]
	v_lshlrev_b64 v[92:93], 11, v[92:93]
	v_ashrrev_i32_e32 v77, 31, v76
	v_lshl_add_u64 v[68:69], v[68:69], 0, s[0:1]
	v_lshl_add_u64 v[44:45], s[20:21], 0, v[44:45]
	v_lshlrev_b64 v[28:29], 11, v[28:29]
	v_ashrrev_i32_e32 v13, 31, v12
	v_lshl_add_u64 v[148:149], v[148:149], 0, s[72:73]
	v_lshl_add_u64 v[108:109], v[108:109], 0, s[0:1]
	v_lshl_add_u64 v[92:93], s[20:21], 0, v[92:93]
	v_lshlrev_b64 v[76:77], 11, v[76:77]
	v_lshl_add_u64 v[68:69], v[68:69], 0, s[72:73]
	v_lshl_add_u64 v[44:45], v[44:45], 0, s[0:1]
	v_lshl_add_u64 v[28:29], s[20:21], 0, v[28:29]
	v_lshlrev_b64 v[12:13], 11, v[12:13]
	v_lshl_add_u64 v[148:149], v[148:149], 0, v[2:3]
	v_cvt_pk_bf16_f32 v115, v110, v111
	v_lshl_add_u64 v[108:109], v[108:109], 0, s[72:73]
	v_lshl_add_u64 v[92:93], v[92:93], 0, s[0:1]
	v_lshl_add_u64 v[76:77], s[20:21], 0, v[76:77]
	v_lshl_add_u64 v[68:69], v[68:69], 0, v[2:3]
	v_cvt_pk_bf16_f32 v51, v46, v47
	v_lshl_add_u64 v[44:45], v[44:45], 0, s[72:73]
	v_lshl_add_u64 v[28:29], v[28:29], 0, s[0:1]
	v_lshl_add_u64 v[12:13], s[20:21], 0, v[12:13]
	global_store_dwordx4 v[148:149], v[112:115], off offset:256
	v_cvt_pk_bf16_f32 v99, v94, v95
	v_lshl_add_u64 v[92:93], v[92:93], 0, s[72:73]
	v_lshl_add_u64 v[112:113], v[108:109], 0, v[2:3]
	v_lshl_add_u64 v[76:77], v[76:77], 0, s[0:1]
	global_store_dwordx4 v[68:69], v[48:51], off offset:256
	v_cvt_pk_bf16_f32 v35, v30, v31
	v_lshl_add_u64 v[28:29], v[28:29], 0, s[72:73]
	v_lshl_add_u64 v[48:49], v[44:45], 0, v[2:3]
	v_lshl_add_u64 v[12:13], v[12:13], 0, s[0:1]
	global_store_dwordx4 v[112:113], v[96:99], off offset:256
	v_cvt_pk_bf16_f32 v83, v78, v79
	v_lshl_add_u64 v[76:77], v[76:77], 0, s[72:73]
	v_lshl_add_u64 v[96:97], v[92:93], 0, v[2:3]
	global_store_dwordx4 v[48:49], v[32:35], off offset:256
	v_cvt_pk_bf16_f32 v23, v14, v15
	v_lshl_add_u64 v[12:13], v[12:13], 0, s[72:73]
	v_lshl_add_u64 v[32:33], v[28:29], 0, v[2:3]
	v_cvt_pk_bf16_f32 v128, v128, v129
	v_cvt_pk_bf16_f32 v129, v130, v131
	v_cvt_pk_bf16_f32 v130, v124, v125
	v_cvt_pk_bf16_f32 v131, v126, v127
	v_cvt_pk_bf16_f32 v108, v120, v121
	v_cvt_pk_bf16_f32 v109, v122, v123
	v_cvt_pk_bf16_f32 v110, v116, v117
	v_cvt_pk_bf16_f32 v111, v118, v119
	v_cvt_pk_bf16_f32 v92, v104, v105
	v_cvt_pk_bf16_f32 v93, v106, v107
	v_cvt_pk_bf16_f32 v94, v100, v101
	v_cvt_pk_bf16_f32 v95, v102, v103
	global_store_dwordx4 v[96:97], v[80:83], off offset:256
	v_cvt_pk_bf16_f32 v78, v84, v85
	v_cvt_pk_bf16_f32 v79, v86, v87
	v_lshl_add_u64 v[80:81], v[76:77], 0, v[2:3]
	v_cvt_pk_bf16_f32 v76, v88, v89
	v_cvt_pk_bf16_f32 v77, v90, v91
	v_cvt_pk_bf16_f32 v75, v70, v71
	v_cvt_pk_bf16_f32 v64, v64, v65
	v_cvt_pk_bf16_f32 v65, v66, v67
	v_cvt_pk_bf16_f32 v66, v60, v61
	v_cvt_pk_bf16_f32 v67, v62, v63
	v_cvt_pk_bf16_f32 v44, v56, v57
	v_cvt_pk_bf16_f32 v45, v58, v59
	v_cvt_pk_bf16_f32 v46, v52, v53
	v_cvt_pk_bf16_f32 v47, v54, v55
	v_cvt_pk_bf16_f32 v28, v40, v41
	v_cvt_pk_bf16_f32 v29, v42, v43
	v_cvt_pk_bf16_f32 v30, v36, v37
	v_cvt_pk_bf16_f32 v31, v38, v39
	global_store_dwordx4 v[32:33], v[20:23], off offset:256
	v_cvt_pk_bf16_f32 v14, v16, v17
	v_cvt_pk_bf16_f32 v15, v18, v19
	v_lshl_add_u64 v[20:21], v[12:13], 0, v[2:3]
	v_cvt_pk_bf16_f32 v12, v24, v25
	v_cvt_pk_bf16_f32 v13, v26, v27
	v_cvt_pk_bf16_f32 v8, v8, v9
	v_cvt_pk_bf16_f32 v9, v10, v11
	v_cvt_pk_bf16_f32 v10, v4, v5
	v_cvt_pk_bf16_f32 v11, v6, v7
	s_and_b64 vcc, exec, s[38:39]
	s_mov_b32 s1, s40
	s_mov_b32 s0, s42
	s_mov_b64 s[50:51], s[46:47]
	s_mov_b64 s[48:49], s[44:45]
	global_store_dwordx4 v[148:149], v[128:131], off
	global_store_dwordx4 v[112:113], v[108:111], off
	global_store_dwordx4 v[96:97], v[92:95], off
	global_store_dwordx4 v[80:81], v[76:79], off
	global_store_dwordx4 v[80:81], v[72:75], off offset:256
	global_store_dwordx4 v[68:69], v[64:67], off
	global_store_dwordx4 v[48:49], v[44:47], off
	global_store_dwordx4 v[32:33], v[28:31], off
	global_store_dwordx4 v[20:21], v[12:15], off
	global_store_dwordx4 v[20:21], v[8:11], off offset:256
	s_cmpk_lt_u32 s31, 0x100
	s_cbranch_scc1 .Lep_b_136
	s_barrier
.Lep_b_136:
	s_cbranch_vccz .LBB0_129
	s_waitcnt vmcnt(0)
	s_cmpk_gt_u32 s31, 0xff
	s_cbranch_scc1 .LBB0_140
	s_barrier
